# w_in weight tiles converted by the workgroups idle in P1's last GEMM round instead of in P0
# baseline (speedup 1.0000x reference)
; #define LAS __attribute__((address_space(3)))
; __device__ __forceinline__ void convert_weights(CArgsP a, LAS unsigned char* lds, int wave, int lane, int which, int gb, int NGB) {
;     unsigned char* ws = a->ws;
;     constexpr int I0 = 22 * 16, I1 = 4 * 44, I2 = 14 * 16, I3 = 4 * 16;
;     const int NIT = which == 0 ? I0 + I1 + I2 : I0 + I1 + I3;
;     for (int it = gb; it < NIT; it += NGB) {
;         int r = it;
;         if (r < I0) { const int pn = r >> 4, kb = r & 15;
;             convert_tile(which == 0 ? a->in[8] : a->in[28], 1024, 5632, which == 0 ? a->in[7] : a->in[27], (bf16_t*)(ws + (which == 0 ? WS_W1I : WS_W2I)), pn, 64 * kb, 0, lds, wave, lane); continue; }
.Lz_done:
	s_load_dwordx2 s[16:17], s[18:19], 0xf8
	v_and_b32_e32 v148, 63, v164
	s_lshr_b32 s79, s44, 6
	s_cmpk_gt_i32 s2, 0x2ef
	v_lshlrev_b32_e32 v165, 2, v148
	v_lshlrev_b32_e32 v150, 3, v164
	s_cbranch_scc1 .LBB0_39
	s_movk_i32 s45, 0x2f0
	s_cmpk_lg_i32 s60, 0x100
	s_cbranch_scc1 .Lp0_bound
	s_movk_i32 s45, 0x210
.Lp0_bound:
	s_lshl_b32 s0, s79, 3
	s_and_b32 s3, s44, 0xc0
	s_and_b32 s12, s0, 0x1fffffe0
	s_or_b32 s6, s0, 24
	s_waitcnt lgkmcnt(0)
	s_add_u32 s22, s16, 0x1400000
	s_addc_u32 s23, s17, 0
	s_or_b32 s7, s0, 1
	s_add_u32 s24, s16, 0xe00000
	s_movk_i32 s4, 0xc0
	v_and_b32_e32 v5, 32, v164
	s_addc_u32 s25, s17, 0
	v_lshlrev_b32_e32 v3, 2, v148
	v_and_or_b32 v45, v150, s4, v5
	s_add_u32 s26, s16, 0x300000
	v_lshrrev_b32_e32 v5, 5, v148
	v_and_b32_e32 v4, 28, v3
	v_or_b32_e32 v43, s3, v148
	s_addc_u32 s27, s17, 0
	v_mul_u32_u24_e32 v5, 0xb00, v5
	s_movk_i32 s4, 0x60
	s_lshl_b32 s13, s2, 4
	v_and_b32_e32 v1, 0xe0, v3
	s_mov_b32 s21, 0
	v_mov_b32_e32 v2, 0
	v_lshl_add_u32 v42, v148, 4, 0
	s_mul_i32 s1, s79, 0x2080
	v_lshl_add_u32 v44, v43, 2, 0
	s_mul_i32 s3, s12, 0x410
	s_mulk_i32 s6, 0x410
	s_mulk_i32 s7, 0x410
	v_and_or_b32 v46, v3, s4, v5
	v_cmp_gt_u32_e64 s[4:5], 8, v4
	s_add_i32 s30, s13, 0xffffdf00
	s_lshl_b32 s31, s60, 4
	s_lshl_b32 s33, s2, 6
	s_lshl_b32 s34, s60, 6
	s_movk_i32 s35, 0xd00
	s_movk_i32 s36, 0x7fff
	s_mov_b32 s37, 0xffff0000
	s_lshl_b32 s20, s12, 1
	v_lshlrev_b32_e32 v38, 2, v4
	v_mov_b32_e32 v47, 0x3420
	v_mov_b32_e32 v48, 0x5800
	s_mov_b32 s38, s2
	s_branch .LBB0_6

; #define LAS __attribute__((address_space(3)))
; __device__ __forceinline__ void convert_tile(const float* __restrict__ W, int K, int ldn, const float* __restrict__ gain, bf16_t* WT, int pn, int k0, int kind, LAS unsigned char* lds, int wave, int lane) {
;     ...
;     u32x4* dst = (u32x4*)(WT + (size_t)(256 * pn + n) * K + k0 + 32 * hf);
; #pragma unroll
;     for (int j = 0; j < 4; ++j) dst[j] = o[j];
; }
; __device__ __forceinline__ void convert_weights(CArgsP a, LAS unsigned char* lds, int wave, int lane, int which, int gb, int NGB) {
;     unsigned char* ws = a->ws;
;     constexpr int I0 = 22 * 16, I1 = 4 * 44, I2 = 14 * 16, I3 = 4 * 16;
;     const int NIT = which == 0 ? I0 + I1 + I2 : I0 + I1 + I3;
;     for (int it = gb; it < NIT; it += NGB) {
.LBB0_5:
	v_mov_b32_e32 v23, v2
	v_lshl_add_u64 v[20:21], v[22:23], 1, v[20:21]
	s_add_i32 s38, s38, s60
	s_add_i32 s30, s30, s31
	s_add_i32 s33, s33, s34
	v_lshl_add_u64 v[20:21], v[20:21], 0, s[20:21]
	s_cmp_lt_i32 s38, s45
	global_store_dwordx4 v[20:21], v[4:7], off
	global_store_dwordx4 v[20:21], v[8:11], off offset:16
	global_store_dwordx4 v[20:21], v[12:15], off offset:32
	global_store_dwordx4 v[20:21], v[16:19], off offset:48
	s_cbranch_scc0 .LBB0_39

; __device__ __forceinline__ void convert_weights(CArgsP a, LAS unsigned char* lds, int wave, int lane, int which, int gb, int NGB) {
;     ...
;     for (int it = gb; it < NIT; it += NGB) {
;         int r = it;
;         if (r < I0) { const int pn = r >> 4, kb = r & 15;
;             convert_tile(which == 0 ? a->in[8] : a->in[28], 1024, 5632, which == 0 ? a->in[7] : a->in[27], (bf16_t*)(ws + (which == 0 ? WS_W1I : WS_W2I)), pn, 64 * kb, 0, lds, wave, lane); continue; }
;         r -= I0;
;         if (r < I1) { const int pn = r / 44, kb = r % 44; convert_tile(which == 0 ? a->in[9] : a->in[29], DFF, 1024, nullptr, (bf16_t*)(ws + (which == 0 ? WS_W1O : WS_W2O)), pn, 64 * kb, 1, lds, wave, lane); continue; }
;         r -= I1;
;         if (which == 0) { const int pn = r >> 4, kb = r & 15; convert_tile(a->in[11], 1024, 3336, a->in[10], (bf16_t*)(ws + WS_WIN), pn, 64 * kb, 2, lds, wave, lane); }
; __global__ void __launch_bounds__(512, 2) mega_fwd(Args a_unused) {
;     ...
;       if (bx >= G - 4) {
.LBB0_124:
	s_add_i32 s77, s60, -4
	s_cmp_ge_i32 s2, s77
	s_cselect_b64 s[80:81], -1, 0
	s_cmp_lt_i32 s2, s77
	s_cbranch_scc0 .Lp1_tail
	s_cmpk_lt_i32 s2, 0x96
	s_cbranch_scc1 .LBB0_225
	s_cmpk_lg_i32 s60, 0x100
	s_cbranch_scc1 .LBB0_225
	v_writelane_b32 v253, s0, 0
	v_writelane_b32 v253, s1, 1
	v_writelane_b32 v253, s2, 2
	v_writelane_b32 v253, s3, 3
	v_writelane_b32 v253, s4, 4
	v_writelane_b32 v253, s5, 5
	v_writelane_b32 v253, s6, 6
	v_writelane_b32 v253, s7, 7
	v_writelane_b32 v253, s12, 8
	v_writelane_b32 v253, s13, 9
	v_writelane_b32 v253, s14, 10
	v_writelane_b32 v253, s15, 11
	v_writelane_b32 v253, s16, 12
	v_writelane_b32 v253, s17, 13
	v_writelane_b32 v253, s18, 14
	v_writelane_b32 v253, s19, 15
	v_writelane_b32 v253, s20, 16
	v_writelane_b32 v253, s21, 17
	v_writelane_b32 v253, s22, 18
	v_writelane_b32 v253, s23, 19
	v_writelane_b32 v253, s24, 20
	v_writelane_b32 v253, s25, 21
	v_writelane_b32 v253, s26, 22
	v_writelane_b32 v253, s27, 23
	v_writelane_b32 v253, s28, 24
	v_writelane_b32 v253, s29, 25
	v_writelane_b32 v253, s30, 26
	v_writelane_b32 v253, s31, 27
	v_writelane_b32 v253, s32, 28
	v_writelane_b32 v253, s33, 29
	v_writelane_b32 v253, s34, 30
	v_writelane_b32 v253, s35, 31
	v_writelane_b32 v253, s36, 32
	v_writelane_b32 v253, s37, 33
	v_writelane_b32 v253, s38, 34
	v_writelane_b32 v253, s39, 35
	v_writelane_b32 v253, s40, 36
	v_writelane_b32 v253, s41, 37
	v_writelane_b32 v253, s42, 38
	v_writelane_b32 v253, s43, 39
	v_writelane_b32 v253, s44, 40
	s_mov_b64 s[18:19], s[92:93]
	s_load_dwordx2 s[16:17], s[92:93], 0xf8
	s_lshl_b32 s0, s79, 3
	s_lshl_b32 s3, s79, 6
	s_and_b32 s3, s3, 0xc0
	s_and_b32 s12, s0, 0x1fffffe0
	s_or_b32 s6, s0, 24
	s_waitcnt lgkmcnt(0)
	s_add_u32 s22, s16, 0x1400000
	s_addc_u32 s23, s17, 0
	s_or_b32 s7, s0, 1
	s_add_u32 s24, s16, 0xe00000
	s_movk_i32 s4, 0xc0
	v_and_b32_e32 v5, 32, v164
	s_addc_u32 s25, s17, 0
	v_lshlrev_b32_e32 v3, 2, v148
	v_and_or_b32 v45, v150, s4, v5
	s_add_u32 s26, s16, 0x300000
	v_lshrrev_b32_e32 v5, 5, v148
	v_and_b32_e32 v4, 28, v3
	v_or_b32_e32 v43, s3, v148
	s_addc_u32 s27, s17, 0
	v_mul_u32_u24_e32 v5, 0xb00, v5
	s_movk_i32 s4, 0x60
	s_add_i32 s13, s2, 378
	s_lshl_b32 s13, s13, 4
	v_and_b32_e32 v1, 0xe0, v3
	s_mov_b32 s21, 0
	v_mov_b32_e32 v2, 0
	v_lshl_add_u32 v42, v148, 4, 0
	s_mul_i32 s1, s79, 0x2080
	v_lshl_add_u32 v44, v43, 2, 0
	s_mul_i32 s3, s12, 0x410
	s_mulk_i32 s6, 0x410
	s_mulk_i32 s7, 0x410
	v_and_or_b32 v46, v3, s4, v5
	v_cmp_gt_u32_e64 s[4:5], 8, v4
	s_add_i32 s30, s13, 0xffffdf00
	s_movk_i32 s31, 0x660
	s_add_i32 s33, s2, 378
	s_lshl_b32 s33, s33, 6
	s_movk_i32 s34, 0x1980
	s_movk_i32 s35, 0xd00
	s_movk_i32 s36, 0x7fff
	s_mov_b32 s37, 0xffff0000
	s_lshl_b32 s20, s12, 1
	v_lshlrev_b32_e32 v38, 2, v4
	v_mov_b32_e32 v47, 0x3420
	v_mov_b32_e32 v48, 0x5800
	s_add_i32 s38, s2, 378
	s_branch .Lp1cv_6

; #define LAS __attribute__((address_space(3)))
; __device__ __forceinline__ void convert_tile(const float* __restrict__ W, int K, int ldn, const float* __restrict__ gain, bf16_t* WT, int pn, int k0, int kind, LAS unsigned char* lds, int wave, int lane) {
;     ...
;     u32x4* dst = (u32x4*)(WT + (size_t)(256 * pn + n) * K + k0 + 32 * hf);
; #pragma unroll
;     for (int j = 0; j < 4; ++j) dst[j] = o[j];
; }
; __device__ __forceinline__ void convert_weights(CArgsP a, LAS unsigned char* lds, int wave, int lane, int which, int gb, int NGB) {
;     unsigned char* ws = a->ws;
;     constexpr int I0 = 22 * 16, I1 = 4 * 44, I2 = 14 * 16, I3 = 4 * 16;
;     const int NIT = which == 0 ? I0 + I1 + I2 : I0 + I1 + I3;
;     for (int it = gb; it < NIT; it += NGB) {
.Lp1cv_5:
	v_mov_b32_e32 v23, v2
	v_lshl_add_u64 v[20:21], v[22:23], 1, v[20:21]
	s_addk_i32 s38, 0x66
	s_add_i32 s30, s30, s31
	s_add_i32 s33, s33, s34
	v_lshl_add_u64 v[20:21], v[20:21], 0, s[20:21]
	s_cmpk_lt_i32 s38, 0x2f0
	global_store_dwordx4 v[20:21], v[4:7], off
	global_store_dwordx4 v[20:21], v[8:11], off offset:16
	global_store_dwordx4 v[20:21], v[12:15], off offset:32
	global_store_dwordx4 v[20:21], v[16:19], off offset:48
	s_cbranch_scc0 .Lp1cv_done

; __device__ __forceinline__ void wait_count(unsigned* cnt, unsigned want) {
;     if (threadIdx.x == 0) {
;         unsigned sp = 0;
;         while (__hip_atomic_load(cnt, __ATOMIC_RELAXED, __HIP_MEMORY_SCOPE_AGENT) < want && ++sp < (1u << 24)) __builtin_amdgcn_s_sleep(2);
;         __builtin_amdgcn_fence(__ATOMIC_ACQUIRE, "agent");
; __global__ void __launch_bounds__(512, 2) mega_fwd(Args a_unused) {
;     ...
;       if (bx >= G - 4) {
;         wait_count(cnt, 8u * (2 * DFF / 256));
.Lp1cv_done:
	v_readlane_b32 s0, v253, 0
	v_readlane_b32 s1, v253, 1
	v_readlane_b32 s2, v253, 2
	v_readlane_b32 s3, v253, 3
	v_readlane_b32 s4, v253, 4
	v_readlane_b32 s5, v253, 5
	v_readlane_b32 s6, v253, 6
	v_readlane_b32 s7, v253, 7
	v_readlane_b32 s12, v253, 8
	v_readlane_b32 s13, v253, 9
	v_readlane_b32 s14, v253, 10
	v_readlane_b32 s15, v253, 11
	v_readlane_b32 s16, v253, 12
	v_readlane_b32 s17, v253, 13
	v_readlane_b32 s18, v253, 14
	v_readlane_b32 s19, v253, 15
	v_readlane_b32 s20, v253, 16
	v_readlane_b32 s21, v253, 17
	v_readlane_b32 s22, v253, 18
	v_readlane_b32 s23, v253, 19
	v_readlane_b32 s24, v253, 20
	v_readlane_b32 s25, v253, 21
	v_readlane_b32 s26, v253, 22
	v_readlane_b32 s27, v253, 23
	v_readlane_b32 s28, v253, 24
	v_readlane_b32 s29, v253, 25
	v_readlane_b32 s30, v253, 26
	v_readlane_b32 s31, v253, 27
	v_readlane_b32 s32, v253, 28
	v_readlane_b32 s33, v253, 29
	v_readlane_b32 s34, v253, 30
	v_readlane_b32 s35, v253, 31
	v_readlane_b32 s36, v253, 32
	v_readlane_b32 s37, v253, 33
	v_readlane_b32 s38, v253, 34
	v_readlane_b32 s39, v253, 35
	v_readlane_b32 s40, v253, 36
	v_readlane_b32 s41, v253, 37
	v_readlane_b32 s42, v253, 38
	v_readlane_b32 s43, v253, 39
	v_readlane_b32 s44, v253, 40
	s_nop 3
	s_branch .LBB0_225
.Lp1_tail:
	s_and_saveexec_b64 s[4:5], s[52:53]
	s_cbranch_execz .LBB0_138
	v_mov_b32_e32 v0, 0
	global_load_dword v1, v0, s[12:13] sc1
	s_movk_i32 s0, 0xaf
	s_waitcnt vmcnt(0)
	v_cmp_lt_u32_e32 vcc, s0, v1
	s_cbranch_vccnz .LBB0_137
	s_mov_b32 s1, 0xfffff8
	s_movk_i32 s3, 0xb0
	s_branch .LBB0_129
